# GLU/pool epilogue: step waits count only the loads (vmcnt(j) with j stores in flight instead of vmcnt(0)); s5_unit prologue: eight parameter loads issued together with counted waits
# speedup vs baseline: 1.0019x; 1.0008x over previous
.LBB0_563:
	v_lshlrev_b64 v[146:147], 12, v[178:179]
	v_lshl_add_u64 v[150:151], s[12:13], 0, v[146:147]
	v_lshl_add_u64 v[146:147], v[150:151], 0, s[8:9]
	v_lshl_add_u64 v[146:147], v[168:169], 1, v[146:147]
	s_and_b64 vcc, exec, s[6:7]
	s_mov_b64 s[8:9], -1
	global_store_dwordx4 v[146:147], v[154:157], off
	s_cbranch_vccnz .LBB0_565
	s_waitcnt vmcnt(1)
	v_pk_mul_f32 v[148:149], v[144:145], v[128:129]
	v_pk_mul_f32 v[146:147], v[142:143], v[126:127]
	s_mov_b64 s[8:9], 0
	v_pk_mul_f32 v[152:153], v[140:141], v[124:125]
	v_pk_mul_f32 v[154:155], v[138:139], v[122:123]
	v_cvt_pk_bf16_f32 v146, v146, v147
	v_cvt_pk_bf16_f32 v147, v148, v149
	v_cvt_pk_bf16_f32 v149, v152, v153
	s_nop 0
	v_cvt_pk_bf16_f32 v148, v154, v155
.LBB0_565:
	s_andn2_b64 vcc, exec, s[8:9]
	s_mov_b64 s[8:9], 0xc00
	s_cbranch_vccnz .LBB0_567
	v_mul_f32_e32 v142, 0xbfb8aa3b, v142
	v_mul_f32_e32 v138, 0xbfb8aa3b, v138
	v_mul_f32_e32 v143, 0xbfb8aa3b, v143
	v_mul_f32_e32 v139, 0xbfb8aa3b, v139
	v_mul_f32_e32 v144, 0xbfb8aa3b, v144
	v_mul_f32_e32 v140, 0xbfb8aa3b, v140
	v_mul_f32_e32 v145, 0xbfb8aa3b, v145
	v_mul_f32_e32 v141, 0xbfb8aa3b, v141
	v_exp_f32_e32 v142, v142
	v_exp_f32_e32 v138, v138
	v_exp_f32_e32 v143, v143
	v_exp_f32_e32 v139, v139
	v_exp_f32_e32 v144, v144
	v_exp_f32_e32 v140, v140
	v_exp_f32_e32 v145, v145
	v_exp_f32_e32 v141, v141
	v_add_f32_e32 v142, 1.0, v142
	v_add_f32_e32 v138, 1.0, v138
	v_add_f32_e32 v143, 1.0, v143
	v_add_f32_e32 v139, 1.0, v139
	v_add_f32_e32 v144, 1.0, v144
	v_add_f32_e32 v140, 1.0, v140
	v_add_f32_e32 v145, 1.0, v145
	v_add_f32_e32 v141, 1.0, v141
	v_rcp_f32_e32 v142, v142
	v_rcp_f32_e32 v138, v138
	v_rcp_f32_e32 v143, v143
	v_rcp_f32_e32 v139, v139
	v_rcp_f32_e32 v144, v144
	v_rcp_f32_e32 v140, v140
	v_rcp_f32_e32 v145, v145
	v_rcp_f32_e32 v141, v141
	s_waitcnt vmcnt(1)
	v_lshlrev_b32_e32 v146, 16, v74
	v_and_b32_e32 v147, 0xffff0000, v74
	v_lshlrev_b32_e32 v148, 16, v75
	v_and_b32_e32 v149, 0xffff0000, v75
	v_lshlrev_b32_e32 v152, 16, v76
	v_and_b32_e32 v153, 0xffff0000, v76
	v_lshlrev_b32_e32 v154, 16, v77
	v_and_b32_e32 v155, 0xffff0000, v77
	s_mov_b64 s[8:9], 0x800
	v_mul_f32_e32 v142, v142, v146
	v_mul_f32_e32 v138, v138, v152
	v_mul_f32_e32 v143, v143, v147
	v_mul_f32_e32 v139, v139, v153
	v_mul_f32_e32 v144, v144, v148
	v_mul_f32_e32 v140, v140, v154
	v_mul_f32_e32 v145, v145, v149
	v_mul_f32_e32 v141, v141, v155
	v_cvt_pk_bf16_f32 v146, v142, v143
	v_cvt_pk_bf16_f32 v147, v144, v145
	v_cvt_pk_bf16_f32 v148, v138, v139
	v_cvt_pk_bf16_f32 v149, v140, v141
.LBB0_567:
	v_add_u32_e32 v144, 16, v178
	v_ashrrev_i32_e32 v145, 31, v144
	v_lshlrev_b64 v[138:139], 12, v[144:145]
	v_lshl_add_u64 v[142:143], s[12:13], 0, v[138:139]
	v_lshl_add_u64 v[138:139], v[142:143], 0, s[8:9]
	v_lshl_add_u64 v[138:139], v[168:169], 1, v[138:139]
	s_and_b64 vcc, exec, s[6:7]
	s_mov_b64 s[8:9], -1
	global_store_dwordx4 v[138:139], v[146:149], off
	s_cbranch_vccnz .LBB0_569
	s_waitcnt vmcnt(2)
	v_pk_mul_f32 v[140:141], v[136:137], v[128:129]
	v_pk_mul_f32 v[138:139], v[134:135], v[126:127]
	s_mov_b64 s[8:9], 0
	v_pk_mul_f32 v[146:147], v[132:133], v[124:125]
	v_pk_mul_f32 v[148:149], v[130:131], v[122:123]
	v_cvt_pk_bf16_f32 v138, v138, v139
	v_cvt_pk_bf16_f32 v139, v140, v141
	v_cvt_pk_bf16_f32 v141, v146, v147
	s_nop 0
	v_cvt_pk_bf16_f32 v140, v148, v149
.LBB0_569:
	s_andn2_b64 vcc, exec, s[8:9]
	s_mov_b64 s[8:9], 0xc00
	s_cbranch_vccnz .LBB0_571
	v_mul_f32_e32 v134, 0xbfb8aa3b, v134
	v_mul_f32_e32 v130, 0xbfb8aa3b, v130
	v_mul_f32_e32 v135, 0xbfb8aa3b, v135
	v_mul_f32_e32 v131, 0xbfb8aa3b, v131
	v_mul_f32_e32 v136, 0xbfb8aa3b, v136
	v_mul_f32_e32 v132, 0xbfb8aa3b, v132
	v_mul_f32_e32 v137, 0xbfb8aa3b, v137
	v_mul_f32_e32 v133, 0xbfb8aa3b, v133
	v_exp_f32_e32 v134, v134
	v_exp_f32_e32 v130, v130
	v_exp_f32_e32 v135, v135
	v_exp_f32_e32 v131, v131
	v_exp_f32_e32 v136, v136
	v_exp_f32_e32 v132, v132
	v_exp_f32_e32 v137, v137
	v_exp_f32_e32 v133, v133
	v_add_f32_e32 v134, 1.0, v134
	v_add_f32_e32 v130, 1.0, v130
	v_add_f32_e32 v135, 1.0, v135
	v_add_f32_e32 v131, 1.0, v131
	v_add_f32_e32 v136, 1.0, v136
	v_add_f32_e32 v132, 1.0, v132
	v_add_f32_e32 v137, 1.0, v137
	v_add_f32_e32 v133, 1.0, v133
	v_rcp_f32_e32 v134, v134
	v_rcp_f32_e32 v130, v130
	v_rcp_f32_e32 v135, v135
	v_rcp_f32_e32 v131, v131
	v_rcp_f32_e32 v136, v136
	v_rcp_f32_e32 v132, v132
	v_rcp_f32_e32 v137, v137
	v_rcp_f32_e32 v133, v133
	s_waitcnt vmcnt(2)
	v_lshlrev_b32_e32 v138, 16, v70
	v_and_b32_e32 v139, 0xffff0000, v70
	v_lshlrev_b32_e32 v140, 16, v71
	v_and_b32_e32 v141, 0xffff0000, v71
	v_lshlrev_b32_e32 v146, 16, v72
	v_and_b32_e32 v147, 0xffff0000, v72
	v_lshlrev_b32_e32 v148, 16, v73
	v_and_b32_e32 v149, 0xffff0000, v73
	s_mov_b64 s[8:9], 0x800
	v_mul_f32_e32 v134, v134, v138
	v_mul_f32_e32 v130, v130, v146
	v_mul_f32_e32 v135, v135, v139
	v_mul_f32_e32 v131, v131, v147
	v_mul_f32_e32 v136, v136, v140
	v_mul_f32_e32 v132, v132, v148
	v_mul_f32_e32 v137, v137, v141
	v_mul_f32_e32 v133, v133, v149
	v_cvt_pk_bf16_f32 v138, v134, v135
	v_cvt_pk_bf16_f32 v139, v136, v137
	v_cvt_pk_bf16_f32 v140, v130, v131
	v_cvt_pk_bf16_f32 v141, v132, v133
.LBB0_571:
	v_add_u32_e32 v136, 32, v178
	v_ashrrev_i32_e32 v137, 31, v136
	v_lshlrev_b64 v[130:131], 12, v[136:137]
	v_lshl_add_u64 v[134:135], s[12:13], 0, v[130:131]
	v_lshl_add_u64 v[130:131], v[134:135], 0, s[8:9]
	v_lshl_add_u64 v[130:131], v[168:169], 1, v[130:131]
	s_and_b64 vcc, exec, s[6:7]
	s_mov_b64 s[8:9], -1
	global_store_dwordx4 v[130:131], v[138:141], off
	s_cbranch_vccnz .LBB0_573
	s_waitcnt vmcnt(3)
	v_pk_mul_f32 v[132:133], v[120:121], v[128:129]
	v_pk_mul_f32 v[130:131], v[118:119], v[126:127]
	s_mov_b64 s[8:9], 0
	v_pk_mul_f32 v[138:139], v[116:117], v[124:125]
	v_pk_mul_f32 v[140:141], v[114:115], v[122:123]
	v_cvt_pk_bf16_f32 v130, v130, v131
	v_cvt_pk_bf16_f32 v131, v132, v133
	v_cvt_pk_bf16_f32 v133, v138, v139
	s_nop 0
	v_cvt_pk_bf16_f32 v132, v140, v141
.LBB0_573:
	s_andn2_b64 vcc, exec, s[8:9]
	s_mov_b64 s[8:9], 0xc00
	s_cbranch_vccnz .LBB0_575
	v_mul_f32_e32 v118, 0xbfb8aa3b, v118
	v_mul_f32_e32 v114, 0xbfb8aa3b, v114
	v_mul_f32_e32 v119, 0xbfb8aa3b, v119
	v_mul_f32_e32 v115, 0xbfb8aa3b, v115
	v_mul_f32_e32 v120, 0xbfb8aa3b, v120
	v_mul_f32_e32 v116, 0xbfb8aa3b, v116
	v_mul_f32_e32 v121, 0xbfb8aa3b, v121
	v_mul_f32_e32 v117, 0xbfb8aa3b, v117
	v_exp_f32_e32 v118, v118
	v_exp_f32_e32 v114, v114
	v_exp_f32_e32 v119, v119
	v_exp_f32_e32 v115, v115
	v_exp_f32_e32 v120, v120
	v_exp_f32_e32 v116, v116
	v_exp_f32_e32 v121, v121
	v_exp_f32_e32 v117, v117
	v_add_f32_e32 v118, 1.0, v118
	v_add_f32_e32 v114, 1.0, v114
	v_add_f32_e32 v119, 1.0, v119
	v_add_f32_e32 v115, 1.0, v115
	v_add_f32_e32 v120, 1.0, v120
	v_add_f32_e32 v116, 1.0, v116
	v_add_f32_e32 v121, 1.0, v121
	v_add_f32_e32 v117, 1.0, v117
	v_rcp_f32_e32 v118, v118
	v_rcp_f32_e32 v114, v114
	v_rcp_f32_e32 v119, v119
	v_rcp_f32_e32 v115, v115
	v_rcp_f32_e32 v120, v120
	v_rcp_f32_e32 v116, v116
	v_rcp_f32_e32 v121, v121
	v_rcp_f32_e32 v117, v117
	s_waitcnt vmcnt(3)
	v_lshlrev_b32_e32 v130, 16, v58
	v_and_b32_e32 v131, 0xffff0000, v58
	v_lshlrev_b32_e32 v132, 16, v59
	v_and_b32_e32 v133, 0xffff0000, v59
	v_lshlrev_b32_e32 v138, 16, v60
	v_and_b32_e32 v139, 0xffff0000, v60
	v_lshlrev_b32_e32 v140, 16, v61
	v_and_b32_e32 v141, 0xffff0000, v61
	s_mov_b64 s[8:9], 0x800
	v_mul_f32_e32 v118, v118, v130
	v_mul_f32_e32 v114, v114, v138
	v_mul_f32_e32 v119, v119, v131
	v_mul_f32_e32 v115, v115, v139
	v_mul_f32_e32 v120, v120, v132
	v_mul_f32_e32 v116, v116, v140
	v_mul_f32_e32 v121, v121, v133
	v_mul_f32_e32 v117, v117, v141
	v_cvt_pk_bf16_f32 v130, v118, v119
	v_cvt_pk_bf16_f32 v131, v120, v121
	v_cvt_pk_bf16_f32 v132, v114, v115
	v_cvt_pk_bf16_f32 v133, v116, v117

.LBB0_585:
	v_lshlrev_b64 v[106:107], 12, v[118:119]
	v_lshl_add_u64 v[110:111], s[12:13], 0, v[106:107]
	v_lshl_add_u64 v[106:107], v[110:111], 0, s[8:9]
	v_lshl_add_u64 v[106:107], v[168:169], 1, v[106:107]
	s_and_b64 vcc, exec, s[6:7]
	s_mov_b64 s[8:9], -1
	global_store_dwordx4 v[106:107], v[114:117], off
	s_cbranch_vccnz .LBB0_587
	s_waitcnt vmcnt(1)
	v_pk_mul_f32 v[108:109], v[104:105], v[128:129]
	v_pk_mul_f32 v[106:107], v[102:103], v[126:127]
	s_mov_b64 s[8:9], 0
	v_pk_mul_f32 v[112:113], v[100:101], v[124:125]
	v_pk_mul_f32 v[114:115], v[98:99], v[122:123]
	v_cvt_pk_bf16_f32 v106, v106, v107
	v_cvt_pk_bf16_f32 v107, v108, v109
	v_cvt_pk_bf16_f32 v109, v112, v113
	s_nop 0
	v_cvt_pk_bf16_f32 v108, v114, v115
.LBB0_587:
	s_andn2_b64 vcc, exec, s[8:9]
	s_mov_b64 s[8:9], 0xc00
	s_cbranch_vccnz .LBB0_589
	v_mul_f32_e32 v102, 0xbfb8aa3b, v102
	v_mul_f32_e32 v98, 0xbfb8aa3b, v98
	v_mul_f32_e32 v103, 0xbfb8aa3b, v103
	v_mul_f32_e32 v99, 0xbfb8aa3b, v99
	v_mul_f32_e32 v104, 0xbfb8aa3b, v104
	v_mul_f32_e32 v100, 0xbfb8aa3b, v100
	v_mul_f32_e32 v105, 0xbfb8aa3b, v105
	v_mul_f32_e32 v101, 0xbfb8aa3b, v101
	v_exp_f32_e32 v102, v102
	v_exp_f32_e32 v98, v98
	v_exp_f32_e32 v103, v103
	v_exp_f32_e32 v99, v99
	v_exp_f32_e32 v104, v104
	v_exp_f32_e32 v100, v100
	v_exp_f32_e32 v105, v105
	v_exp_f32_e32 v101, v101
	v_add_f32_e32 v102, 1.0, v102
	v_add_f32_e32 v98, 1.0, v98
	v_add_f32_e32 v103, 1.0, v103
	v_add_f32_e32 v99, 1.0, v99
	v_add_f32_e32 v104, 1.0, v104
	v_add_f32_e32 v100, 1.0, v100
	v_add_f32_e32 v105, 1.0, v105
	v_add_f32_e32 v101, 1.0, v101
	v_rcp_f32_e32 v102, v102
	v_rcp_f32_e32 v98, v98
	v_rcp_f32_e32 v103, v103
	v_rcp_f32_e32 v99, v99
	v_rcp_f32_e32 v104, v104
	v_rcp_f32_e32 v100, v100
	v_rcp_f32_e32 v105, v105
	v_rcp_f32_e32 v101, v101
	s_waitcnt vmcnt(1)
	v_lshlrev_b32_e32 v106, 16, v74
	v_and_b32_e32 v107, 0xffff0000, v74
	v_lshlrev_b32_e32 v108, 16, v75
	v_and_b32_e32 v109, 0xffff0000, v75
	v_lshlrev_b32_e32 v112, 16, v76
	v_and_b32_e32 v113, 0xffff0000, v76
	v_lshlrev_b32_e32 v114, 16, v77
	v_and_b32_e32 v115, 0xffff0000, v77
	s_mov_b64 s[8:9], 0x800
	v_mul_f32_e32 v102, v102, v106
	v_mul_f32_e32 v98, v98, v112
	v_mul_f32_e32 v103, v103, v107
	v_mul_f32_e32 v99, v99, v113
	v_mul_f32_e32 v104, v104, v108
	v_mul_f32_e32 v100, v100, v114
	v_mul_f32_e32 v105, v105, v109
	v_mul_f32_e32 v101, v101, v115
	v_cvt_pk_bf16_f32 v106, v102, v103
	v_cvt_pk_bf16_f32 v107, v104, v105
	v_cvt_pk_bf16_f32 v108, v98, v99
	v_cvt_pk_bf16_f32 v109, v100, v101
.LBB0_589:
	v_add_u32_e32 v104, 0x90, v178
	v_ashrrev_i32_e32 v105, 31, v104
	v_lshlrev_b64 v[98:99], 12, v[104:105]
	v_lshl_add_u64 v[102:103], s[12:13], 0, v[98:99]
	v_lshl_add_u64 v[98:99], v[102:103], 0, s[8:9]
	v_lshl_add_u64 v[98:99], v[168:169], 1, v[98:99]
	s_and_b64 vcc, exec, s[6:7]
	s_mov_b64 s[8:9], -1
	global_store_dwordx4 v[98:99], v[106:109], off
	s_cbranch_vccnz .LBB0_591
	s_waitcnt vmcnt(2)
	v_pk_mul_f32 v[100:101], v[96:97], v[128:129]
	v_pk_mul_f32 v[98:99], v[94:95], v[126:127]
	s_mov_b64 s[8:9], 0
	v_pk_mul_f32 v[106:107], v[92:93], v[124:125]
	v_pk_mul_f32 v[108:109], v[90:91], v[122:123]
	v_cvt_pk_bf16_f32 v98, v98, v99
	v_cvt_pk_bf16_f32 v99, v100, v101
	v_cvt_pk_bf16_f32 v101, v106, v107
	s_nop 0
	v_cvt_pk_bf16_f32 v100, v108, v109
.LBB0_591:
	s_andn2_b64 vcc, exec, s[8:9]
	s_mov_b64 s[8:9], 0xc00
	s_cbranch_vccnz .LBB0_593
	v_mul_f32_e32 v94, 0xbfb8aa3b, v94
	v_mul_f32_e32 v90, 0xbfb8aa3b, v90
	v_mul_f32_e32 v95, 0xbfb8aa3b, v95
	v_mul_f32_e32 v91, 0xbfb8aa3b, v91
	v_mul_f32_e32 v96, 0xbfb8aa3b, v96
	v_mul_f32_e32 v92, 0xbfb8aa3b, v92
	v_mul_f32_e32 v97, 0xbfb8aa3b, v97
	v_mul_f32_e32 v93, 0xbfb8aa3b, v93
	v_exp_f32_e32 v94, v94
	v_exp_f32_e32 v90, v90
	v_exp_f32_e32 v95, v95
	v_exp_f32_e32 v91, v91
	v_exp_f32_e32 v96, v96
	v_exp_f32_e32 v92, v92
	v_exp_f32_e32 v97, v97
	v_exp_f32_e32 v93, v93
	v_add_f32_e32 v94, 1.0, v94
	v_add_f32_e32 v90, 1.0, v90
	v_add_f32_e32 v95, 1.0, v95
	v_add_f32_e32 v91, 1.0, v91
	v_add_f32_e32 v96, 1.0, v96
	v_add_f32_e32 v92, 1.0, v92
	v_add_f32_e32 v97, 1.0, v97
	v_add_f32_e32 v93, 1.0, v93
	v_rcp_f32_e32 v94, v94
	v_rcp_f32_e32 v90, v90
	v_rcp_f32_e32 v95, v95
	v_rcp_f32_e32 v91, v91
	v_rcp_f32_e32 v96, v96
	v_rcp_f32_e32 v92, v92
	v_rcp_f32_e32 v97, v97
	v_rcp_f32_e32 v93, v93
	s_waitcnt vmcnt(2)
	v_lshlrev_b32_e32 v98, 16, v70
	v_and_b32_e32 v99, 0xffff0000, v70
	v_lshlrev_b32_e32 v100, 16, v71
	v_and_b32_e32 v101, 0xffff0000, v71
	v_lshlrev_b32_e32 v106, 16, v72
	v_and_b32_e32 v107, 0xffff0000, v72
	v_lshlrev_b32_e32 v108, 16, v73
	v_and_b32_e32 v109, 0xffff0000, v73
	s_mov_b64 s[8:9], 0x800
	v_mul_f32_e32 v94, v94, v98
	v_mul_f32_e32 v90, v90, v106
	v_mul_f32_e32 v95, v95, v99
	v_mul_f32_e32 v91, v91, v107
	v_mul_f32_e32 v96, v96, v100
	v_mul_f32_e32 v92, v92, v108
	v_mul_f32_e32 v97, v97, v101
	v_mul_f32_e32 v93, v93, v109
	v_cvt_pk_bf16_f32 v98, v94, v95
	v_cvt_pk_bf16_f32 v99, v96, v97
	v_cvt_pk_bf16_f32 v100, v90, v91
	v_cvt_pk_bf16_f32 v101, v92, v93
.LBB0_593:
	v_add_u32_e32 v106, 0xa0, v178
	v_ashrrev_i32_e32 v107, 31, v106
	v_lshlrev_b64 v[90:91], 12, v[106:107]
	v_lshl_add_u64 v[94:95], s[12:13], 0, v[90:91]
	v_lshl_add_u64 v[90:91], v[94:95], 0, s[8:9]
	v_lshl_add_u64 v[90:91], v[168:169], 1, v[90:91]
	s_and_b64 vcc, exec, s[6:7]
	s_mov_b64 s[8:9], -1
	global_store_dwordx4 v[90:91], v[98:101], off
	s_cbranch_vccnz .LBB0_595
	s_waitcnt vmcnt(3)
	v_pk_mul_f32 v[92:93], v[84:85], v[128:129]
	v_pk_mul_f32 v[90:91], v[82:83], v[126:127]
	s_mov_b64 s[8:9], 0
	v_pk_mul_f32 v[96:97], v[80:81], v[124:125]
	v_pk_mul_f32 v[98:99], v[78:79], v[122:123]
	v_cvt_pk_bf16_f32 v90, v90, v91
	v_cvt_pk_bf16_f32 v91, v92, v93
	v_cvt_pk_bf16_f32 v93, v96, v97
	s_nop 0
	v_cvt_pk_bf16_f32 v92, v98, v99
.LBB0_595:
	s_andn2_b64 vcc, exec, s[8:9]
	s_mov_b64 s[8:9], 0xc00
	s_cbranch_vccnz .LBB0_597
	v_mul_f32_e32 v82, 0xbfb8aa3b, v82
	v_mul_f32_e32 v78, 0xbfb8aa3b, v78
	v_mul_f32_e32 v83, 0xbfb8aa3b, v83
	v_mul_f32_e32 v79, 0xbfb8aa3b, v79
	v_mul_f32_e32 v84, 0xbfb8aa3b, v84
	v_mul_f32_e32 v80, 0xbfb8aa3b, v80
	v_mul_f32_e32 v85, 0xbfb8aa3b, v85
	v_mul_f32_e32 v81, 0xbfb8aa3b, v81
	v_exp_f32_e32 v82, v82
	v_exp_f32_e32 v78, v78
	v_exp_f32_e32 v83, v83
	v_exp_f32_e32 v79, v79
	v_exp_f32_e32 v84, v84
	v_exp_f32_e32 v80, v80
	v_exp_f32_e32 v85, v85
	v_exp_f32_e32 v81, v81
	v_add_f32_e32 v82, 1.0, v82
	v_add_f32_e32 v78, 1.0, v78
	v_add_f32_e32 v83, 1.0, v83
	v_add_f32_e32 v79, 1.0, v79
	v_add_f32_e32 v84, 1.0, v84
	v_add_f32_e32 v80, 1.0, v80
	v_add_f32_e32 v85, 1.0, v85
	v_add_f32_e32 v81, 1.0, v81
	v_rcp_f32_e32 v82, v82
	v_rcp_f32_e32 v78, v78
	v_rcp_f32_e32 v83, v83
	v_rcp_f32_e32 v79, v79
	v_rcp_f32_e32 v84, v84
	v_rcp_f32_e32 v80, v80
	v_rcp_f32_e32 v85, v85
	v_rcp_f32_e32 v81, v81
	s_waitcnt vmcnt(3)
	v_lshlrev_b32_e32 v90, 16, v58
	v_and_b32_e32 v91, 0xffff0000, v58
	v_lshlrev_b32_e32 v92, 16, v59
	v_and_b32_e32 v93, 0xffff0000, v59
	v_lshlrev_b32_e32 v96, 16, v60
	v_and_b32_e32 v97, 0xffff0000, v60
	v_lshlrev_b32_e32 v98, 16, v61
	v_and_b32_e32 v99, 0xffff0000, v61
	s_mov_b64 s[8:9], 0x800
	v_mul_f32_e32 v82, v82, v90
	v_mul_f32_e32 v78, v78, v96
	v_mul_f32_e32 v83, v83, v91
	v_mul_f32_e32 v79, v79, v97
	v_mul_f32_e32 v84, v84, v92
	v_mul_f32_e32 v80, v80, v98
	v_mul_f32_e32 v85, v85, v93
	v_mul_f32_e32 v81, v81, v99
	v_cvt_pk_bf16_f32 v90, v82, v83
	v_cvt_pk_bf16_f32 v91, v84, v85
	v_cvt_pk_bf16_f32 v92, v78, v79
	v_cvt_pk_bf16_f32 v93, v80, v81

.LBB0_603:
	v_lshl_add_u64 v[62:63], v[150:151], 0, s[24:25]
	v_lshl_add_u64 v[62:63], v[168:169], 1, v[62:63]
	s_and_b64 vcc, exec, s[6:7]
	s_mov_b64 s[24:25], -1
	global_store_dwordx4 v[62:63], v[90:93], off offset:64
	s_cbranch_vccnz .LBB0_605
	s_waitcnt vmcnt(1)
	v_pk_mul_f32 v[64:65], v[56:57], v[84:85]
	v_pk_mul_f32 v[62:63], v[54:55], v[82:83]
	s_mov_b64 s[24:25], 0
	v_pk_mul_f32 v[66:67], v[52:53], v[80:81]
	v_pk_mul_f32 v[68:69], v[50:51], v[78:79]
	v_cvt_pk_bf16_f32 v62, v62, v63
	v_cvt_pk_bf16_f32 v63, v64, v65
	v_cvt_pk_bf16_f32 v65, v66, v67
	s_nop 0
	v_cvt_pk_bf16_f32 v64, v68, v69
.LBB0_605:
	s_andn2_b64 vcc, exec, s[24:25]
	s_mov_b64 s[24:25], 0xc00
	s_cbranch_vccnz .LBB0_607
	v_mul_f32_e32 v54, 0xbfb8aa3b, v54
	v_mul_f32_e32 v50, 0xbfb8aa3b, v50
	v_mul_f32_e32 v55, 0xbfb8aa3b, v55
	v_mul_f32_e32 v51, 0xbfb8aa3b, v51
	v_mul_f32_e32 v56, 0xbfb8aa3b, v56
	v_mul_f32_e32 v52, 0xbfb8aa3b, v52
	v_mul_f32_e32 v57, 0xbfb8aa3b, v57
	v_mul_f32_e32 v53, 0xbfb8aa3b, v53
	v_exp_f32_e32 v54, v54
	v_exp_f32_e32 v50, v50
	v_exp_f32_e32 v55, v55
	v_exp_f32_e32 v51, v51
	v_exp_f32_e32 v56, v56
	v_exp_f32_e32 v52, v52
	v_exp_f32_e32 v57, v57
	v_exp_f32_e32 v53, v53
	v_add_f32_e32 v54, 1.0, v54
	v_add_f32_e32 v50, 1.0, v50
	v_add_f32_e32 v55, 1.0, v55
	v_add_f32_e32 v51, 1.0, v51
	v_add_f32_e32 v56, 1.0, v56
	v_add_f32_e32 v52, 1.0, v52
	v_add_f32_e32 v57, 1.0, v57
	v_add_f32_e32 v53, 1.0, v53
	v_rcp_f32_e32 v54, v54
	v_rcp_f32_e32 v50, v50
	v_rcp_f32_e32 v55, v55
	v_rcp_f32_e32 v51, v51
	v_rcp_f32_e32 v56, v56
	v_rcp_f32_e32 v52, v52
	v_rcp_f32_e32 v57, v57
	v_rcp_f32_e32 v53, v53
	s_waitcnt vmcnt(1)
	v_lshlrev_b32_e32 v62, 16, v74
	v_and_b32_e32 v63, 0xffff0000, v74
	v_lshlrev_b32_e32 v64, 16, v75
	v_and_b32_e32 v65, 0xffff0000, v75
	v_lshlrev_b32_e32 v66, 16, v76
	v_and_b32_e32 v67, 0xffff0000, v76
	v_lshlrev_b32_e32 v68, 16, v77
	v_and_b32_e32 v69, 0xffff0000, v77
	s_mov_b64 s[24:25], 0x800
	v_mul_f32_e32 v54, v54, v62
	v_mul_f32_e32 v50, v50, v66
	v_mul_f32_e32 v55, v55, v63
	v_mul_f32_e32 v51, v51, v67
	v_mul_f32_e32 v56, v56, v64
	v_mul_f32_e32 v52, v52, v68
	v_mul_f32_e32 v57, v57, v65
	v_mul_f32_e32 v53, v53, v69
	v_cvt_pk_bf16_f32 v62, v54, v55
	v_cvt_pk_bf16_f32 v63, v56, v57
	v_cvt_pk_bf16_f32 v64, v50, v51
	v_cvt_pk_bf16_f32 v65, v52, v53
.LBB0_607:
	v_lshl_add_u64 v[50:51], v[142:143], 0, s[24:25]
	v_lshl_add_u64 v[50:51], v[168:169], 1, v[50:51]
	s_and_b64 vcc, exec, s[6:7]
	s_mov_b64 s[24:25], -1
	global_store_dwordx4 v[50:51], v[62:65], off offset:64
	s_cbranch_vccnz .LBB0_609
	s_waitcnt vmcnt(2)
	v_pk_mul_f32 v[52:53], v[48:49], v[84:85]
	v_pk_mul_f32 v[50:51], v[46:47], v[82:83]
	s_mov_b64 s[24:25], 0
	v_pk_mul_f32 v[54:55], v[44:45], v[80:81]
	v_pk_mul_f32 v[56:57], v[42:43], v[78:79]
	v_cvt_pk_bf16_f32 v50, v50, v51
	v_cvt_pk_bf16_f32 v51, v52, v53
	v_cvt_pk_bf16_f32 v53, v54, v55
	s_nop 0
	v_cvt_pk_bf16_f32 v52, v56, v57
.LBB0_609:
	s_andn2_b64 vcc, exec, s[24:25]
	s_mov_b64 s[24:25], 0xc00
	s_cbranch_vccnz .LBB0_611
	v_mul_f32_e32 v46, 0xbfb8aa3b, v46
	v_mul_f32_e32 v42, 0xbfb8aa3b, v42
	v_mul_f32_e32 v47, 0xbfb8aa3b, v47
	v_mul_f32_e32 v43, 0xbfb8aa3b, v43
	v_mul_f32_e32 v48, 0xbfb8aa3b, v48
	v_mul_f32_e32 v44, 0xbfb8aa3b, v44
	v_mul_f32_e32 v49, 0xbfb8aa3b, v49
	v_mul_f32_e32 v45, 0xbfb8aa3b, v45
	v_exp_f32_e32 v46, v46
	v_exp_f32_e32 v42, v42
	v_exp_f32_e32 v47, v47
	v_exp_f32_e32 v43, v43
	v_exp_f32_e32 v48, v48
	v_exp_f32_e32 v44, v44
	v_exp_f32_e32 v49, v49
	v_exp_f32_e32 v45, v45
	v_add_f32_e32 v46, 1.0, v46
	v_add_f32_e32 v42, 1.0, v42
	v_add_f32_e32 v47, 1.0, v47
	v_add_f32_e32 v43, 1.0, v43
	v_add_f32_e32 v48, 1.0, v48
	v_add_f32_e32 v44, 1.0, v44
	v_add_f32_e32 v49, 1.0, v49
	v_add_f32_e32 v45, 1.0, v45
	v_rcp_f32_e32 v46, v46
	v_rcp_f32_e32 v42, v42
	v_rcp_f32_e32 v47, v47
	v_rcp_f32_e32 v43, v43
	v_rcp_f32_e32 v48, v48
	v_rcp_f32_e32 v44, v44
	v_rcp_f32_e32 v49, v49
	v_rcp_f32_e32 v45, v45
	s_waitcnt vmcnt(2)
	v_lshlrev_b32_e32 v50, 16, v70
	v_and_b32_e32 v51, 0xffff0000, v70
	v_lshlrev_b32_e32 v52, 16, v71
	v_and_b32_e32 v53, 0xffff0000, v71
	v_lshlrev_b32_e32 v54, 16, v72
	v_and_b32_e32 v55, 0xffff0000, v72
	v_lshlrev_b32_e32 v56, 16, v73
	v_and_b32_e32 v57, 0xffff0000, v73
	s_mov_b64 s[24:25], 0x800
	v_mul_f32_e32 v46, v46, v50
	v_mul_f32_e32 v42, v42, v54
	v_mul_f32_e32 v47, v47, v51
	v_mul_f32_e32 v43, v43, v55
	v_mul_f32_e32 v48, v48, v52
	v_mul_f32_e32 v44, v44, v56
	v_mul_f32_e32 v49, v49, v53
	v_mul_f32_e32 v45, v45, v57
	v_cvt_pk_bf16_f32 v50, v46, v47
	v_cvt_pk_bf16_f32 v51, v48, v49
	v_cvt_pk_bf16_f32 v52, v42, v43
	v_cvt_pk_bf16_f32 v53, v44, v45
.LBB0_611:
	v_lshl_add_u64 v[42:43], v[134:135], 0, s[24:25]
	v_lshl_add_u64 v[42:43], v[168:169], 1, v[42:43]
	s_and_b64 vcc, exec, s[6:7]
	s_mov_b64 s[24:25], -1
	global_store_dwordx4 v[42:43], v[50:53], off offset:64
	s_cbranch_vccnz .LBB0_613
	s_waitcnt vmcnt(3)
	v_pk_mul_f32 v[44:45], v[40:41], v[84:85]
	v_pk_mul_f32 v[42:43], v[38:39], v[82:83]
	s_mov_b64 s[24:25], 0
	v_pk_mul_f32 v[46:47], v[36:37], v[80:81]
	v_pk_mul_f32 v[48:49], v[34:35], v[78:79]
	v_cvt_pk_bf16_f32 v42, v42, v43
	v_cvt_pk_bf16_f32 v43, v44, v45
	v_cvt_pk_bf16_f32 v45, v46, v47
	s_nop 0
	v_cvt_pk_bf16_f32 v44, v48, v49
.LBB0_613:
	s_andn2_b64 vcc, exec, s[24:25]
	s_mov_b64 s[24:25], 0xc00
	s_cbranch_vccnz .LBB0_615
	v_mul_f32_e32 v38, 0xbfb8aa3b, v38
	v_mul_f32_e32 v34, 0xbfb8aa3b, v34
	v_mul_f32_e32 v39, 0xbfb8aa3b, v39
	v_mul_f32_e32 v35, 0xbfb8aa3b, v35
	v_mul_f32_e32 v40, 0xbfb8aa3b, v40
	v_mul_f32_e32 v36, 0xbfb8aa3b, v36
	v_mul_f32_e32 v41, 0xbfb8aa3b, v41
	v_mul_f32_e32 v37, 0xbfb8aa3b, v37
	v_exp_f32_e32 v38, v38
	v_exp_f32_e32 v34, v34
	v_exp_f32_e32 v39, v39
	v_exp_f32_e32 v35, v35
	v_exp_f32_e32 v40, v40
	v_exp_f32_e32 v36, v36
	v_exp_f32_e32 v41, v41
	v_exp_f32_e32 v37, v37
	v_add_f32_e32 v38, 1.0, v38
	v_add_f32_e32 v34, 1.0, v34
	v_add_f32_e32 v39, 1.0, v39
	v_add_f32_e32 v35, 1.0, v35
	v_add_f32_e32 v40, 1.0, v40
	v_add_f32_e32 v36, 1.0, v36
	v_add_f32_e32 v41, 1.0, v41
	v_add_f32_e32 v37, 1.0, v37
	v_rcp_f32_e32 v38, v38
	v_rcp_f32_e32 v34, v34
	v_rcp_f32_e32 v39, v39
	v_rcp_f32_e32 v35, v35
	v_rcp_f32_e32 v40, v40
	v_rcp_f32_e32 v36, v36
	v_rcp_f32_e32 v41, v41
	v_rcp_f32_e32 v37, v37
	s_waitcnt vmcnt(3)
	v_lshlrev_b32_e32 v42, 16, v58
	v_and_b32_e32 v43, 0xffff0000, v58
	v_lshlrev_b32_e32 v44, 16, v59
	v_and_b32_e32 v45, 0xffff0000, v59
	v_lshlrev_b32_e32 v46, 16, v60
	v_and_b32_e32 v47, 0xffff0000, v60
	v_lshlrev_b32_e32 v48, 16, v61
	v_and_b32_e32 v49, 0xffff0000, v61
	s_mov_b64 s[24:25], 0x800
	v_mul_f32_e32 v38, v38, v42
	v_mul_f32_e32 v34, v34, v46
	v_mul_f32_e32 v39, v39, v43
	v_mul_f32_e32 v35, v35, v47
	v_mul_f32_e32 v40, v40, v44
	v_mul_f32_e32 v36, v36, v48
	v_mul_f32_e32 v41, v41, v45
	v_mul_f32_e32 v37, v37, v49
	v_cvt_pk_bf16_f32 v42, v38, v39
	v_cvt_pk_bf16_f32 v43, v40, v41
	v_cvt_pk_bf16_f32 v44, v34, v35
	v_cvt_pk_bf16_f32 v45, v36, v37

.LBB0_619:
	v_lshl_add_u64 v[26:27], v[110:111], 0, s[8:9]
	v_lshl_add_u64 v[26:27], v[168:169], 1, v[26:27]
	s_and_b64 vcc, exec, s[6:7]
	s_mov_b64 s[8:9], -1
	global_store_dwordx4 v[26:27], v[34:37], off offset:64
	s_cbranch_vccnz .LBB0_621
	s_waitcnt vmcnt(1)
	v_pk_mul_f32 v[28:29], v[24:25], v[84:85]
	v_pk_mul_f32 v[26:27], v[22:23], v[82:83]
	s_mov_b64 s[8:9], 0
	v_pk_mul_f32 v[30:31], v[20:21], v[80:81]
	v_pk_mul_f32 v[32:33], v[18:19], v[78:79]
	v_cvt_pk_bf16_f32 v26, v26, v27
	v_cvt_pk_bf16_f32 v27, v28, v29
	v_cvt_pk_bf16_f32 v29, v30, v31
	s_nop 0
	v_cvt_pk_bf16_f32 v28, v32, v33
.LBB0_621:
	s_andn2_b64 vcc, exec, s[8:9]
	s_mov_b64 s[8:9], 0xc00
	s_cbranch_vccnz .LBB0_623
	v_mul_f32_e32 v22, 0xbfb8aa3b, v22
	v_mul_f32_e32 v18, 0xbfb8aa3b, v18
	v_mul_f32_e32 v23, 0xbfb8aa3b, v23
	v_mul_f32_e32 v19, 0xbfb8aa3b, v19
	v_mul_f32_e32 v24, 0xbfb8aa3b, v24
	v_mul_f32_e32 v20, 0xbfb8aa3b, v20
	v_mul_f32_e32 v25, 0xbfb8aa3b, v25
	v_mul_f32_e32 v21, 0xbfb8aa3b, v21
	v_exp_f32_e32 v22, v22
	v_exp_f32_e32 v18, v18
	v_exp_f32_e32 v23, v23
	v_exp_f32_e32 v19, v19
	v_exp_f32_e32 v24, v24
	v_exp_f32_e32 v20, v20
	v_exp_f32_e32 v25, v25
	v_exp_f32_e32 v21, v21
	v_add_f32_e32 v22, 1.0, v22
	v_add_f32_e32 v18, 1.0, v18
	v_add_f32_e32 v23, 1.0, v23
	v_add_f32_e32 v19, 1.0, v19
	v_add_f32_e32 v24, 1.0, v24
	v_add_f32_e32 v20, 1.0, v20
	v_add_f32_e32 v25, 1.0, v25
	v_add_f32_e32 v21, 1.0, v21
	v_rcp_f32_e32 v22, v22
	v_rcp_f32_e32 v18, v18
	v_rcp_f32_e32 v23, v23
	v_rcp_f32_e32 v19, v19
	v_rcp_f32_e32 v24, v24
	v_rcp_f32_e32 v20, v20
	v_rcp_f32_e32 v25, v25
	v_rcp_f32_e32 v21, v21
	s_waitcnt vmcnt(1)
	v_lshlrev_b32_e32 v26, 16, v74
	v_and_b32_e32 v27, 0xffff0000, v74
	v_lshlrev_b32_e32 v28, 16, v75
	v_and_b32_e32 v29, 0xffff0000, v75
	v_lshlrev_b32_e32 v30, 16, v76
	v_and_b32_e32 v31, 0xffff0000, v76
	v_lshlrev_b32_e32 v32, 16, v77
	v_and_b32_e32 v33, 0xffff0000, v77
	s_mov_b64 s[8:9], 0x800
	v_mul_f32_e32 v22, v22, v26
	v_mul_f32_e32 v18, v18, v30
	v_mul_f32_e32 v23, v23, v27
	v_mul_f32_e32 v19, v19, v31
	v_mul_f32_e32 v24, v24, v28
	v_mul_f32_e32 v20, v20, v32
	v_mul_f32_e32 v25, v25, v29
	v_mul_f32_e32 v21, v21, v33
	v_cvt_pk_bf16_f32 v26, v22, v23
	v_cvt_pk_bf16_f32 v27, v24, v25
	v_cvt_pk_bf16_f32 v28, v18, v19
	v_cvt_pk_bf16_f32 v29, v20, v21
.LBB0_623:
	v_lshl_add_u64 v[18:19], v[102:103], 0, s[8:9]
	v_lshl_add_u64 v[18:19], v[168:169], 1, v[18:19]
	s_and_b64 vcc, exec, s[6:7]
	s_mov_b64 s[8:9], -1
	global_store_dwordx4 v[18:19], v[26:29], off offset:64
	s_cbranch_vccnz .LBB0_625
	s_waitcnt vmcnt(2)
	v_pk_mul_f32 v[20:21], v[14:15], v[84:85]
	v_pk_mul_f32 v[18:19], v[12:13], v[82:83]
	s_mov_b64 s[8:9], 0
	v_pk_mul_f32 v[22:23], v[10:11], v[80:81]
	v_pk_mul_f32 v[24:25], v[8:9], v[78:79]
	v_cvt_pk_bf16_f32 v18, v18, v19
	v_cvt_pk_bf16_f32 v19, v20, v21
	v_cvt_pk_bf16_f32 v21, v22, v23
	s_nop 0
	v_cvt_pk_bf16_f32 v20, v24, v25
.LBB0_625:
	s_andn2_b64 vcc, exec, s[8:9]
	s_mov_b64 s[8:9], 0xc00
	s_cbranch_vccnz .LBB0_627
	v_mul_f32_e32 v12, 0xbfb8aa3b, v12
	v_mul_f32_e32 v8, 0xbfb8aa3b, v8
	v_mul_f32_e32 v13, 0xbfb8aa3b, v13
	v_mul_f32_e32 v9, 0xbfb8aa3b, v9
	v_mul_f32_e32 v14, 0xbfb8aa3b, v14
	v_mul_f32_e32 v10, 0xbfb8aa3b, v10
	v_mul_f32_e32 v15, 0xbfb8aa3b, v15
	v_mul_f32_e32 v11, 0xbfb8aa3b, v11
	v_exp_f32_e32 v12, v12
	v_exp_f32_e32 v8, v8
	v_exp_f32_e32 v13, v13
	v_exp_f32_e32 v9, v9
	v_exp_f32_e32 v14, v14
	v_exp_f32_e32 v10, v10
	v_exp_f32_e32 v15, v15
	v_exp_f32_e32 v11, v11
	v_add_f32_e32 v12, 1.0, v12
	v_add_f32_e32 v8, 1.0, v8
	v_add_f32_e32 v13, 1.0, v13
	v_add_f32_e32 v9, 1.0, v9
	v_add_f32_e32 v14, 1.0, v14
	v_add_f32_e32 v10, 1.0, v10
	v_add_f32_e32 v15, 1.0, v15
	v_add_f32_e32 v11, 1.0, v11
	v_rcp_f32_e32 v12, v12
	v_rcp_f32_e32 v8, v8
	v_rcp_f32_e32 v13, v13
	v_rcp_f32_e32 v9, v9
	v_rcp_f32_e32 v14, v14
	v_rcp_f32_e32 v10, v10
	v_rcp_f32_e32 v15, v15
	v_rcp_f32_e32 v11, v11
	s_waitcnt vmcnt(2)
	v_lshlrev_b32_e32 v18, 16, v70
	v_and_b32_e32 v19, 0xffff0000, v70
	v_lshlrev_b32_e32 v20, 16, v71
	v_and_b32_e32 v21, 0xffff0000, v71
	v_lshlrev_b32_e32 v22, 16, v72
	v_and_b32_e32 v23, 0xffff0000, v72
	v_lshlrev_b32_e32 v24, 16, v73
	v_and_b32_e32 v25, 0xffff0000, v73
	s_mov_b64 s[8:9], 0x800
	v_mul_f32_e32 v12, v12, v18
	v_mul_f32_e32 v8, v8, v22
	v_mul_f32_e32 v13, v13, v19
	v_mul_f32_e32 v9, v9, v23
	v_mul_f32_e32 v14, v14, v20
	v_mul_f32_e32 v10, v10, v24
	v_mul_f32_e32 v15, v15, v21
	v_mul_f32_e32 v11, v11, v25
	v_cvt_pk_bf16_f32 v18, v12, v13
	v_cvt_pk_bf16_f32 v19, v14, v15
	v_cvt_pk_bf16_f32 v20, v8, v9
	v_cvt_pk_bf16_f32 v21, v10, v11
.LBB0_627:
	v_lshl_add_u64 v[8:9], v[94:95], 0, s[8:9]
	v_lshl_add_u64 v[8:9], v[168:169], 1, v[8:9]
	s_and_b64 vcc, exec, s[6:7]
	s_mov_b64 s[6:7], -1
	global_store_dwordx4 v[8:9], v[18:21], off offset:64
	s_cbranch_vccnz .LBB0_629
	s_waitcnt vmcnt(3)
	v_pk_mul_f32 v[10:11], v[6:7], v[84:85]
	v_pk_mul_f32 v[8:9], v[4:5], v[82:83]
	s_mov_b64 s[6:7], 0
	v_pk_mul_f32 v[12:13], v[2:3], v[80:81]
	v_pk_mul_f32 v[14:15], v[0:1], v[78:79]
	v_cvt_pk_bf16_f32 v8, v8, v9
	v_cvt_pk_bf16_f32 v9, v10, v11
	v_cvt_pk_bf16_f32 v11, v12, v13
	s_nop 0
	v_cvt_pk_bf16_f32 v10, v14, v15
.LBB0_629:
	s_andn2_b64 vcc, exec, s[6:7]
	s_mov_b64 s[6:7], 0xc00
	s_cbranch_vccnz .LBB0_631
	v_mul_f32_e32 v4, 0xbfb8aa3b, v4
	v_mul_f32_e32 v0, 0xbfb8aa3b, v0
	v_mul_f32_e32 v5, 0xbfb8aa3b, v5
	v_mul_f32_e32 v1, 0xbfb8aa3b, v1
	v_mul_f32_e32 v6, 0xbfb8aa3b, v6
	v_mul_f32_e32 v2, 0xbfb8aa3b, v2
	v_mul_f32_e32 v7, 0xbfb8aa3b, v7
	v_mul_f32_e32 v3, 0xbfb8aa3b, v3
	v_exp_f32_e32 v4, v4
	v_exp_f32_e32 v0, v0
	v_exp_f32_e32 v5, v5
	v_exp_f32_e32 v1, v1
	v_exp_f32_e32 v6, v6
	v_exp_f32_e32 v2, v2
	v_exp_f32_e32 v7, v7
	v_exp_f32_e32 v3, v3
	v_add_f32_e32 v4, 1.0, v4
	v_add_f32_e32 v0, 1.0, v0
	v_add_f32_e32 v5, 1.0, v5
	v_add_f32_e32 v1, 1.0, v1
	v_add_f32_e32 v6, 1.0, v6
	v_add_f32_e32 v2, 1.0, v2
	v_add_f32_e32 v7, 1.0, v7
	v_add_f32_e32 v3, 1.0, v3
	v_rcp_f32_e32 v4, v4
	v_rcp_f32_e32 v0, v0
	v_rcp_f32_e32 v5, v5
	v_rcp_f32_e32 v1, v1
	v_rcp_f32_e32 v6, v6
	v_rcp_f32_e32 v2, v2
	v_rcp_f32_e32 v7, v7
	v_rcp_f32_e32 v3, v3
	s_waitcnt vmcnt(3)
	v_lshlrev_b32_e32 v8, 16, v58
	v_and_b32_e32 v9, 0xffff0000, v58
	v_lshlrev_b32_e32 v10, 16, v59
	v_and_b32_e32 v11, 0xffff0000, v59
	v_lshlrev_b32_e32 v12, 16, v60
	v_and_b32_e32 v13, 0xffff0000, v60
	v_lshlrev_b32_e32 v14, 16, v61
	v_and_b32_e32 v15, 0xffff0000, v61
	s_mov_b64 s[6:7], 0x800
	v_mul_f32_e32 v4, v4, v8
	v_mul_f32_e32 v0, v0, v12
	v_mul_f32_e32 v5, v5, v9
	v_mul_f32_e32 v1, v1, v13
	v_mul_f32_e32 v6, v6, v10
	v_mul_f32_e32 v2, v2, v14
	v_mul_f32_e32 v7, v7, v11
	v_mul_f32_e32 v3, v3, v15
	v_cvt_pk_bf16_f32 v8, v4, v5
	v_cvt_pk_bf16_f32 v9, v6, v7
	v_cvt_pk_bf16_f32 v10, v0, v1
	v_cvt_pk_bf16_f32 v11, v2, v3

.LBB0_952:
	s_or_b64 exec, exec, s[0:1]
	s_waitcnt vmcnt(0)
	v_mul_f32_e32 v7, v5, v7
	v_mul_f32_e32 v10, 0x3fb8aa3b, v7
	s_mov_b32 s0, 0x3fb8aa3b
	v_fma_f32 v11, v7, s0, -v10
	v_rndne_f32_e32 v14, v10
	v_fmac_f32_e32 v11, 0x32a5705f, v7
	v_sub_f32_e32 v10, v10, v14
	v_add_f32_e32 v10, v10, v11
	v_exp_f32_e32 v10, v10
	v_cvt_i32_f32_e32 v11, v14
	s_mov_b32 s0, 0xc2ce8ed0
	v_cmp_ngt_f32_e32 vcc, s0, v7
	s_mov_b32 s0, 0x42b17218
	v_ldexp_f32 v10, v10, v11
	v_cndmask_b32_e32 v10, 0, v10, vcc
	v_cmp_nlt_f32_e32 vcc, s0, v7
	s_brev_b32 s0, 1
	v_and_b32_e32 v65, 15, v2
	v_cndmask_b32_e32 v7, v220, v10, vcc
	v_mul_f32_e32 v10, v9, v9
	v_fmamk_f32 v11, v10, 0xb94c1982, v217
	v_fmaak_f32 v11, v10, v11, 0xbe2aaa9d
	v_mul_f32_e32 v11, v10, v11
	v_fmac_f32_e32 v9, v9, v11
	v_fmamk_f32 v11, v10, 0x37d75334, v218
	v_fmaak_f32 v11, v10, v11, 0x3d2aabf7
	v_fmaak_f32 v11, v10, v11, 0xbf000004
	v_fma_f32 v10, v10, v11, 1.0
	v_and_b32_e32 v11, 1, v8
	v_cmp_eq_u32_e32 vcc, 0, v11
	v_lshlrev_b32_e32 v8, 30, v8
	v_and_b32_e32 v50, 48, v2
	v_cndmask_b32_e64 v9, -v9, v10, vcc
	v_bitop3_b32 v8, v8, v9, s0 bitop3:0x6c
	s_movk_i32 s0, 0x1f8
	v_cmp_class_f32_e64 vcc, v3, s0
	v_xor_b32_e32 v3, v6, v3
	v_mov_b32_e32 v51, v17
	v_cndmask_b32_e32 v8, v226, v8, vcc
	v_mul_f32_e32 v54, v7, v8
	v_mul_f32_e32 v8, v13, v13
	v_fmamk_f32 v9, v8, 0xb94c1982, v217
	v_fmaak_f32 v9, v8, v9, 0xbe2aaa9d
	v_mul_f32_e32 v9, v8, v9
	v_fmac_f32_e32 v13, v13, v9
	v_fmamk_f32 v9, v8, 0x37d75334, v218
	v_fmaak_f32 v9, v8, v9, 0x3d2aabf7
	v_fmaak_f32 v9, v8, v9, 0xbf000004
	v_fma_f32 v8, v8, v9, 1.0
	v_and_b32_e32 v9, 1, v12
	v_cmp_eq_u32_e64 s[0:1], 0, v9
	v_lshlrev_b32_e32 v9, 30, v12
	v_and_b32_e32 v9, 0x80000000, v9
	v_cndmask_b32_e64 v8, v8, v13, s[0:1]
	v_xor_b32_e32 v3, v3, v9
	v_xor_b32_e32 v3, v3, v8
	s_lshl_b64 s[0:1], s[20:21], 12
	v_cndmask_b32_e32 v3, v226, v3, vcc
	v_lshl_or_b32 v10, v65, 8, s0
	v_mov_b32_e32 v11, s1
	v_mul_f32_e32 v56, v7, v3
	v_lshl_add_u64 v[6:7], s[14:15], 0, v[10:11]
	v_lshl_add_u64 v[10:11], s[16:17], 0, v[10:11]
	v_lshl_add_u64 v[14:15], v[10:11], 0, v[50:51]
	global_load_dwordx4 v[10:13], v[14:15], off
	v_lshl_add_u64 v[2:3], v[6:7], 0, v[50:51]
	global_load_dwordx4 v[6:9], v[2:3], off
	global_load_dwordx4 v[176:179], v[14:15], off offset:64
	global_load_dwordx4 v[180:183], v[2:3], off offset:64
	global_load_dwordx4 v[184:187], v[14:15], off offset:128
	global_load_dwordx4 v[188:191], v[2:3], off offset:128
	global_load_dwordx4 v[192:195], v[14:15], off offset:192
	global_load_dwordx4 v[196:199], v[2:3], off offset:192
	s_waitcnt vmcnt(6)
	v_cvt_pk_bf16_f32 v40, v6, 0
	v_cvt_pk_bf16_f32 v42, v7, 0
	v_cvt_pk_bf16_f32 v44, v8, 0
	v_cvt_pk_bf16_f32 v46, v9, 0
	s_lshl_b32 s25, s36, 4
	s_or_b32 s0, s25, s27
	s_cmp_lt_u32 s35, 64
	s_cselect_b64 s[2:3], -1, 0
	s_cmp_gt_u32 s35, 63
	v_xor_b32_e32 v6, 0x80000000, v10
	v_cvt_pk_bf16_f32 v41, v6, 0
	v_xor_b32_e32 v6, 0x80000000, v11
	v_cvt_pk_bf16_f32 v43, v6, 0
	v_xor_b32_e32 v6, 0x80000000, v12
	v_cvt_pk_bf16_f32 v45, v6, 0
	v_xor_b32_e32 v6, 0x80000000, v13
	s_waitcnt vmcnt(4)
	v_mov_b32_e32 v10, v176
	v_mov_b32_e32 v11, v177
	v_mov_b32_e32 v12, v178
	v_mov_b32_e32 v13, v179
	v_cvt_pk_bf16_f32 v47, v6, 0
	v_mov_b32_e32 v6, v180
	v_mov_b32_e32 v7, v181
	v_mov_b32_e32 v8, v182
	v_mov_b32_e32 v9, v183
	v_cvt_pk_bf16_f32 v48, v6, 0
	v_cvt_pk_bf16_f32 v51, v7, 0
	v_cvt_pk_bf16_f32 v53, v8, 0
	v_cvt_pk_bf16_f32 v63, v9, 0
	v_xor_b32_e32 v6, 0x80000000, v10
	v_cvt_pk_bf16_f32 v49, v6, 0
	v_xor_b32_e32 v6, 0x80000000, v11
	v_cvt_pk_bf16_f32 v52, v6, 0
	v_xor_b32_e32 v6, 0x80000000, v12
	v_cvt_pk_bf16_f32 v62, v6, 0
	v_xor_b32_e32 v6, 0x80000000, v13
	s_waitcnt vmcnt(2)
	v_mov_b32_e32 v10, v184
	v_mov_b32_e32 v11, v185
	v_mov_b32_e32 v12, v186
	v_mov_b32_e32 v13, v187
	v_cvt_pk_bf16_f32 v69, v6, 0
	v_mov_b32_e32 v6, v188
	v_mov_b32_e32 v7, v189
	v_mov_b32_e32 v8, v190
	v_mov_b32_e32 v9, v191
	v_cvt_pk_bf16_f32 v70, v6, 0
	v_cvt_pk_bf16_f32 v73, v7, 0
	v_cvt_pk_bf16_f32 v77, v8, 0
	v_cvt_pk_bf16_f32 v80, v9, 0
	v_xor_b32_e32 v6, 0x80000000, v10
	v_cvt_pk_bf16_f32 v72, v6, 0
	v_xor_b32_e32 v6, 0x80000000, v11
	v_cvt_pk_bf16_f32 v75, v6, 0
	v_xor_b32_e32 v6, 0x80000000, v12
	v_cvt_pk_bf16_f32 v78, v6, 0
	v_xor_b32_e32 v6, 0x80000000, v13
	s_waitcnt vmcnt(0)
	v_mov_b32_e32 v10, v192
	v_mov_b32_e32 v11, v193
	v_mov_b32_e32 v12, v194
	v_mov_b32_e32 v13, v195
	v_cvt_pk_bf16_f32 v82, v6, 0
	v_mov_b32_e32 v6, v196
	v_mov_b32_e32 v7, v197
	v_mov_b32_e32 v8, v198
	v_mov_b32_e32 v9, v199
	v_cvt_pk_bf16_f32 v74, v6, 0
	v_cvt_pk_bf16_f32 v79, v7, 0
	v_cvt_pk_bf16_f32 v83, v8, 0
	v_cvt_pk_bf16_f32 v85, v9, 0
	v_xor_b32_e32 v2, 0x80000000, v10
	v_cvt_pk_bf16_f32 v76, v2, 0
	v_xor_b32_e32 v2, 0x80000000, v11
	v_cvt_pk_bf16_f32 v81, v2, 0
	v_xor_b32_e32 v2, 0x80000000, v12
	v_cvt_pk_bf16_f32 v84, v2, 0
	v_xor_b32_e32 v2, 0x80000000, v13
	v_cvt_pk_bf16_f32 v86, v2, 0
	v_or_b32_e32 v2, s0, v65
	v_ashrrev_i32_e32 v3, 31, v2
	v_lshl_add_u64 v[2:3], v[2:3], 2, s[18:19]
	global_load_dword v66, v[2:3], off
	s_cbranch_scc1 .LBB0_954
	v_mul_f32_e32 v2, v4, v4
	v_fmac_f32_e32 v2, v5, v5
	v_div_scale_f32 v3, s[0:1], v2, v2, 1.0
	v_rcp_f32_e32 v6, v3
	v_add_f32_e32 v15, -1.0, v54
	v_fma_f32 v7, -v3, v6, 1.0
	v_fmac_f32_e32 v6, v7, v6
	v_div_scale_f32 v7, vcc, 1.0, v2, 1.0
	v_mul_f32_e32 v8, v7, v6
	v_fma_f32 v9, -v3, v8, v7
	v_fmac_f32_e32 v8, v9, v6
	v_fma_f32 v3, -v3, v8, v7
	v_div_fmas_f32 v3, v3, v6, v8
	v_div_fixup_f32 v14, v3, v2, 1.0
	v_mul_f32_e32 v2, v4, v15
	v_lshlrev_b64 v[6:7], 6, v[0:1]
	v_mul_f32_e32 v4, v4, v56
	v_fma_f32 v2, v5, v56, -v2
	v_lshl_add_u64 v[12:13], s[10:11], 0, v[6:7]
	v_fmac_f32_e32 v4, v5, v15
	v_lshl_add_u64 v[30:31], s[12:13], 0, v[6:7]
	v_mul_f32_e32 v16, v14, v2
	global_load_dwordx4 v[0:3], v[12:13], off
	global_load_dwordx4 v[8:11], v[12:13], off offset:16
	global_load_dwordx4 v[18:21], v[12:13], off offset:32
	global_load_dwordx4 v[22:25], v[12:13], off offset:48
	v_mul_f32_e32 v34, v14, v4
	global_load_dwordx4 v[4:7], v[30:31], off
	global_load_dwordx4 v[12:15], v[30:31], off offset:16
	global_load_dwordx4 v[26:29], v[30:31], off offset:32
	s_nop 0
	global_load_dwordx4 v[30:33], v[30:31], off offset:48
	s_waitcnt vmcnt(0)
	v_mul_f32_e32 v35, v34, v33
	v_mul_f32_e32 v33, v16, v33
	v_fmac_f32_e32 v35, v16, v25
	v_fma_f32 v25, v34, v25, -v33
	v_mul_f32_e32 v33, v34, v32
	v_mul_f32_e32 v32, v16, v32
	v_fmac_f32_e32 v33, v16, v24
	v_fma_f32 v24, v34, v24, -v32
	v_mul_f32_e32 v32, v34, v31
	v_mul_f32_e32 v31, v16, v31
	v_fmac_f32_e32 v32, v16, v23
	v_fma_f32 v23, v34, v23, -v31
	v_mul_f32_e32 v31, v34, v30
	v_mul_f32_e32 v30, v16, v30
	v_fmac_f32_e32 v31, v16, v22
	v_fma_f32 v22, v34, v22, -v30
	v_mul_f32_e32 v30, v34, v29
	v_mul_f32_e32 v29, v16, v29
	v_fmac_f32_e32 v30, v16, v21
	v_fma_f32 v21, v34, v21, -v29
	v_mul_f32_e32 v29, v34, v28
	v_mul_f32_e32 v28, v16, v28
	v_fmac_f32_e32 v29, v16, v20
	v_fma_f32 v20, v34, v20, -v28
	v_mul_f32_e32 v28, v34, v27
	v_mul_f32_e32 v27, v16, v27
	v_fmac_f32_e32 v28, v16, v19
	v_fma_f32 v19, v34, v19, -v27
	v_mul_f32_e32 v27, v34, v26
	v_mul_f32_e32 v26, v16, v26
	v_fmac_f32_e32 v27, v16, v18
	v_fma_f32 v18, v34, v18, -v26
	v_mul_f32_e32 v26, v34, v15
	v_mul_f32_e32 v15, v16, v15
	v_fmac_f32_e32 v26, v16, v11
	v_fma_f32 v11, v34, v11, -v15
	v_mul_f32_e32 v15, v34, v14
	v_mul_f32_e32 v14, v16, v14
	v_fmac_f32_e32 v15, v16, v10
	v_fma_f32 v10, v34, v10, -v14
	v_mul_f32_e32 v14, v34, v13
	v_mul_f32_e32 v13, v16, v13
	v_fmac_f32_e32 v14, v16, v9
	v_fma_f32 v9, v34, v9, -v13
	v_mul_f32_e32 v13, v34, v12
	v_mul_f32_e32 v12, v16, v12
	v_fmac_f32_e32 v13, v16, v8
	v_fma_f32 v8, v34, v8, -v12
	v_mul_f32_e32 v12, v34, v7
	v_mul_f32_e32 v7, v16, v7
	v_fmac_f32_e32 v12, v16, v3
	v_fma_f32 v3, v34, v3, -v7
	v_mul_f32_e32 v7, v34, v6
	v_mul_f32_e32 v6, v16, v6
	v_fmac_f32_e32 v7, v16, v2
	v_fma_f32 v2, v34, v2, -v6
	v_mul_f32_e32 v6, v34, v5
	v_mul_f32_e32 v5, v16, v5
	v_fmac_f32_e32 v6, v16, v1
	v_fma_f32 v1, v34, v1, -v5
	v_mul_f32_e32 v5, v34, v4
	v_mul_f32_e32 v4, v16, v4
	v_fmac_f32_e32 v5, v16, v0
	v_fma_f32 v0, v34, v0, -v4
	v_lshl_add_u32 v4, v64, 5, 0
	v_add_u32_e32 v4, 0x14800, v4
	v_cvt_pk_bf16_f32 v0, v0, v1
	v_cvt_pk_bf16_f32 v1, v2, v3
	v_cvt_pk_bf16_f32 v2, v8, v9
	v_cvt_pk_bf16_f32 v3, v10, v11
	ds_write_b128 v4, v[0:3]
	v_cvt_pk_bf16_f32 v0, v5, v6
	v_cvt_pk_bf16_f32 v1, v7, v12
	v_cvt_pk_bf16_f32 v2, v13, v14
	v_cvt_pk_bf16_f32 v3, v15, v26
	ds_write_b128 v4, v[0:3] offset:2048
	v_cvt_pk_bf16_f32 v0, v18, v19
	v_cvt_pk_bf16_f32 v1, v20, v21
	v_cvt_pk_bf16_f32 v2, v22, v23
	v_cvt_pk_bf16_f32 v3, v24, v25
	ds_write_b128 v4, v[0:3] offset:16
	v_cvt_pk_bf16_f32 v0, v27, v28
	v_cvt_pk_bf16_f32 v1, v29, v30
	v_cvt_pk_bf16_f32 v2, v31, v32
	v_cvt_pk_bf16_f32 v3, v33, v35
	ds_write_b128 v4, v[0:3] offset:2064
